# LayerNorm loop: all 16 row loads issued at iteration top (12 hoisted into spare registers, copied at original sites), removed exposed vmcnt(0) (stacked on v9)
# baseline (speedup 1.0000x reference)
; DI void ln_phase(int wv, const bf16_t* y, float* xo, const float* g, const float* bta, bf16_t* xb) {
;     ...
;     for (int row0 = bid * 8 + wid; row0 < M_TOK; row0 += R * nw) {
;         u32x4 raw[R][2], rsd[R][2];
; #pragma unroll
;         for (int r = 0; r < R; ++r) { const int row = (row0 + r * nw < M_TOK) ? row0 + r * nw : row0;
; #pragma unroll
;             for (int j = 0; j < 2; ++j) { raw[r][j] = *(const u32x4*)(y + (size_t)row * DM + j * 512 + lane * 8); rsd[r][j] = *(const u32x4*)(xb + (size_t)row * DM + j * 512 + lane * 8); } }
; #pragma unroll
;         for (int r = 0; r < R; ++r) {
;             const int row = row0 + r * nw;
;             if (row < M_TOK) {
;                 f32x4 v[4];
; #pragma unroll
;                 for (int j = 0; j < 2; ++j) { const u32x4 q = raw[r][j], x_ = rsd[r][j];
;                     v[2 * j] = (f32x4){__uint_as_float(q.x << 16), __uint_as_float(q.x & 0xffff0000u), __uint_as_float(q.y << 16), __uint_as_float(q.y & 0xffff0000u)}
;                              + (f32x4){__uint_as_float(x_.x << 16), __uint_as_float(x_.x & 0xffff0000u), __uint_as_float(x_.y << 16), __uint_as_float(x_.y & 0xffff0000u)} * ALPHA_RES;
;                     v[2 * j + 1] = (f32x4){__uint_as_float(q.z << 16), __uint_as_float(q.z & 0xffff0000u), __uint_as_float(q.w << 16), __uint_as_float(q.w & 0xffff0000u)}
;                                  + (f32x4){__uint_as_float(x_.z << 16), __uint_as_float(x_.z & 0xffff0000u), __uint_as_float(x_.w << 16), __uint_as_float(x_.w & 0xffff0000u)} * ALPHA_RES; }
;                 float s_ = 0.f;
; #pragma unroll
;                 for (int j = 0; j < 4; ++j) s_ += (v[j].x + v[j].y) + (v[j].z + v[j].w);
;                 const float mean = wave_sum(s_) * (1.f / DM); float s2 = 0.f;
.LBB0_586:
	v_ashrrev_i32_e32 v83, 31, v82
	s_waitcnt vmcnt(0)
	v_lshlrev_b64 v[38:39], 11, v[82:83]
	v_lshl_add_u64 v[42:43], v[90:91], 0, v[38:39]
	global_load_dwordx4 v[34:37], v[42:43], off
	s_nop 0
	v_lshl_add_u64 v[102:103], v[92:93], 0, v[38:39]
	global_load_dwordx4 v[38:41], v[102:103], off
	s_nop 0
	global_load_dwordx4 v[42:45], v[42:43], off offset:1024
	s_nop 0
	global_load_dwordx4 v[46:49], v[102:103], off offset:1024
	s_mul_i32 s0, s46, 24
	v_add_u32_e32 v98, s0, v82
	v_cmp_gt_i32_e64 s[8:9], s71, v98
	v_add_u32_e32 v96, s47, v82
	v_add_u32_e32 v100, s36, v82
	v_cmp_gt_i32_e64 s[6:7], s71, v96
	v_cmp_gt_i32_e64 s[4:5], s71, v100
	s_nop 1
	v_cndmask_b32_e64 v148, v82, v96, s[6:7]
	v_cndmask_b32_e64 v150, v82, v100, s[4:5]
	v_cndmask_b32_e64 v152, v82, v98, s[8:9]
	v_ashrrev_i32_e32 v149, 31, v148
	v_ashrrev_i32_e32 v151, 31, v150
	v_ashrrev_i32_e32 v153, 31, v152
	v_lshlrev_b64 v[148:149], 11, v[148:149]
	v_lshlrev_b64 v[150:151], 11, v[150:151]
	v_lshlrev_b64 v[152:153], 11, v[152:153]
	v_lshl_add_u64 v[154:155], v[90:91], 0, v[148:149]
	v_lshl_add_u64 v[148:149], v[92:93], 0, v[148:149]
	v_lshl_add_u64 v[156:157], v[90:91], 0, v[150:151]
	v_lshl_add_u64 v[150:151], v[92:93], 0, v[150:151]
	v_lshl_add_u64 v[158:159], v[90:91], 0, v[152:153]
	v_lshl_add_u64 v[152:153], v[92:93], 0, v[152:153]
	global_load_dwordx4 v[176:179], v[154:155], off
	global_load_dwordx4 v[180:183], v[154:155], off offset:1024
	global_load_dwordx4 v[184:187], v[148:149], off
	global_load_dwordx4 v[188:191], v[148:149], off offset:1024
	global_load_dwordx4 v[192:195], v[156:157], off
	global_load_dwordx4 v[196:199], v[156:157], off offset:1024
	global_load_dwordx4 v[200:203], v[150:151], off
	global_load_dwordx4 v[204:207], v[150:151], off offset:1024
	global_load_dwordx4 v[208:211], v[158:159], off
	global_load_dwordx4 v[212:215], v[158:159], off offset:1024
	global_load_dwordx4 v[216:219], v[152:153], off
	global_load_dwordx4 v[220:223], v[152:153], off offset:1024
	s_waitcnt vmcnt(14)
	v_lshlrev_b32_e32 v56, 16, v38
	v_lshlrev_b32_e32 v54, 16, v34
	v_and_b32_e32 v55, 0xffff0000, v34
	v_lshlrev_b32_e32 v34, 16, v35
	v_and_b32_e32 v35, 0xffff0000, v35
	v_and_b32_e32 v57, 0xffff0000, v38
	v_lshlrev_b32_e32 v38, 16, v39
	v_and_b32_e32 v39, 0xffff0000, v39
	v_lshlrev_b32_e32 v58, 16, v36
	v_and_b32_e32 v59, 0xffff0000, v36
	v_lshlrev_b32_e32 v36, 16, v37
	v_and_b32_e32 v37, 0xffff0000, v37
	v_lshlrev_b32_e32 v60, 16, v40
	v_and_b32_e32 v61, 0xffff0000, v40
	v_lshlrev_b32_e32 v40, 16, v41
	v_and_b32_e32 v41, 0xffff0000, v41
	v_pk_fma_f32 v[84:85], v[38:39], s[70:71], v[34:35] op_sel_hi:[1,0,1]
	v_pk_fma_f32 v[112:113], v[56:57], s[70:71], v[54:55] op_sel_hi:[1,0,1]
	v_pk_fma_f32 v[86:87], v[40:41], s[70:71], v[36:37] op_sel_hi:[1,0,1]
	v_pk_fma_f32 v[88:89], v[60:61], s[70:71], v[58:59] op_sel_hi:[1,0,1]
	v_pk_mov_b32 v[34:35], v[112:113], v[84:85] op_sel:[1,0]
	v_mov_b32_e32 v36, v112
	v_mov_b32_e32 v37, v85
	v_pk_mov_b32 v[38:39], v[88:89], v[86:87] op_sel:[1,0]
	v_mov_b32_e32 v40, v88
	v_mov_b32_e32 v41, v87
	s_waitcnt vmcnt(13)
	v_lshlrev_b32_e32 v62, 16, v42
	v_and_b32_e32 v63, 0xffff0000, v42
	v_lshlrev_b32_e32 v42, 16, v43
	v_and_b32_e32 v43, 0xffff0000, v43
	s_waitcnt vmcnt(12)
	v_lshlrev_b32_e32 v64, 16, v46
	v_and_b32_e32 v65, 0xffff0000, v46
	v_lshlrev_b32_e32 v46, 16, v47
	v_and_b32_e32 v47, 0xffff0000, v47
	v_lshlrev_b32_e32 v66, 16, v44
	v_and_b32_e32 v67, 0xffff0000, v44
	v_lshlrev_b32_e32 v44, 16, v45
	v_and_b32_e32 v45, 0xffff0000, v45
	v_lshlrev_b32_e32 v68, 16, v48
	v_and_b32_e32 v69, 0xffff0000, v48
	v_lshlrev_b32_e32 v48, 16, v49
	v_and_b32_e32 v49, 0xffff0000, v49
	v_pk_add_f32 v[34:35], v[34:35], v[36:37]
	v_pk_add_f32 v[36:37], v[38:39], v[40:41]
	v_pk_fma_f32 v[108:109], v[46:47], s[70:71], v[42:43] op_sel_hi:[1,0,1]
	v_pk_fma_f32 v[110:111], v[64:65], s[70:71], v[62:63] op_sel_hi:[1,0,1]
	v_pk_fma_f32 v[104:105], v[48:49], s[70:71], v[44:45] op_sel_hi:[1,0,1]
	v_pk_fma_f32 v[106:107], v[68:69], s[70:71], v[66:67] op_sel_hi:[1,0,1]
	v_add_f32_e32 v0, v34, v35
	v_pk_add_f32 v[34:35], v[36:37], v[36:37] op_sel_hi:[0,1]
	v_add_f32_e32 v43, v110, v111
	v_add_f32_e32 v45, v108, v109
	v_mov_b32_e32 v42, v106
	v_mov_b32_e32 v44, v107
	v_mov_b32_e32 v46, v105
	v_add_f32_e32 v47, 0, v0
	v_mov_b32_e32 v34, v104
	v_pk_add_f32 v[38:39], v[42:43], v[44:45]
	v_pk_add_f32 v[34:35], v[34:35], v[46:47]
	v_cndmask_b32_e64 v50, v82, v96, s[6:7]
	v_pk_add_f32 v[34:35], v[38:39], v[34:35]
	v_cndmask_b32_e64 v52, v82, v100, s[4:5]
	v_add_f32_e32 v0, v34, v35
	ds_bpermute_b32 v35, v233, v0
	v_cndmask_b32_e64 v34, v82, v98, s[8:9]
	v_ashrrev_i32_e32 v51, 31, v50
	v_ashrrev_i32_e32 v53, 31, v52
	v_lshlrev_b64 v[36:37], 11, v[50:51]
	s_waitcnt lgkmcnt(0)
	v_add_f32_e32 v0, v0, v35
	ds_bpermute_b32 v40, v234, v0
	v_ashrrev_i32_e32 v35, 31, v34
	v_lshlrev_b64 v[34:35], 11, v[34:35]
	v_lshl_add_u64 v[114:115], v[92:93], 0, v[34:35]
	v_lshlrev_b64 v[38:39], 11, v[52:53]
	s_waitcnt lgkmcnt(0)
	v_add_f32_e32 v0, v0, v40
	ds_bpermute_b32 v44, v235, v0
	v_lshl_add_u64 v[40:41], v[90:91], 0, v[36:37]
	v_lshl_add_u64 v[36:37], v[92:93], 0, v[36:37]
	v_lshl_add_u64 v[42:43], v[90:91], 0, v[38:39]
	s_waitcnt vmcnt(0)
	v_mov_b32_e32 v74, v176
	v_mov_b32_e32 v75, v177
	v_mov_b32_e32 v76, v178
	v_mov_b32_e32 v77, v179
	v_mov_b32_e32 v66, v180
	v_mov_b32_e32 v67, v181
	v_mov_b32_e32 v68, v182
	v_mov_b32_e32 v69, v183
	s_waitcnt lgkmcnt(0)
; DI unsigned pk2(float lo, float hi) { f32x2 f = {lo, hi}; bf2_t v = __builtin_convertvector(f, bf2_t); return __builtin_bit_cast(unsigned, v); }
; DI void ln_phase(int wv, const bf16_t* y, float* xo, const float* g, const float* bta, bf16_t* xb) {
;     ...
;                 const float mean = wave_sum(s_) * (1.f / DM); float s2 = 0.f;
; #pragma unroll
;                 for (int j = 0; j < 4; ++j) { v[j] = v[j] - mean; s2 += (v[j].x * v[j].x + v[j].y * v[j].y) + (v[j].z * v[j].z + v[j].w * v[j].w); }
;                 const float rstd = 1.f / sqrtf(wave_sum(s2) * (1.f / DM) + 1e-5f);
; #pragma unroll
;                 for (int j = 0; j < 2; ++j) { const f32x4 y0 = v[2 * j] * rstd * gv[2 * j] + bv[2 * j], y1 = v[2 * j + 1] * rstd * gv[2 * j + 1] + bv[2 * j + 1];
;                     if (xo) { *(f32x4*)(xo + (size_t)row * DM + j * 512 + lane * 8) = y0; *(f32x4*)(xo + (size_t)row * DM + j * 512 + lane * 8 + 4) = y1; }
;                     u32x4 w; w.x = pk2(y0.x, y0.y); w.y = pk2(y0.z, y0.w); w.z = pk2(y1.x, y1.y); w.w = pk2(y1.z, y1.w);
;                     *(u32x4*)(xb + (size_t)row * DM + j * 512 + lane * 8) = w; }
	v_add_f32_e32 v0, v0, v44
	ds_bpermute_b32 v46, v236, v0
	v_lshl_add_u64 v[44:45], v[90:91], 0, v[34:35]
	v_mov_b32_e32 v78, v184
	v_mov_b32_e32 v79, v185
	v_mov_b32_e32 v80, v186
	v_mov_b32_e32 v81, v187
	v_mov_b32_e32 v70, v188
	v_mov_b32_e32 v71, v189
	v_mov_b32_e32 v72, v190
	v_mov_b32_e32 v73, v191
	v_mov_b32_e32 v58, v192
	v_mov_b32_e32 v59, v193
	v_mov_b32_e32 v60, v194
	v_mov_b32_e32 v61, v195
	v_mov_b32_e32 v50, v196
	v_mov_b32_e32 v51, v197
	v_mov_b32_e32 v52, v198
	v_mov_b32_e32 v53, v199
	v_lshl_add_u64 v[38:39], v[92:93], 0, v[38:39]
	v_lshlrev_b64 v[82:83], 12, v[82:83]
	s_waitcnt lgkmcnt(0)
	v_add_f32_e32 v0, v0, v46
	ds_bpermute_b32 v34, v237, v0
	s_waitcnt lgkmcnt(0)
	v_add_f32_e32 v0, v0, v34
	ds_bpermute_b32 v42, v238, v0
	v_mov_b32_e32 v62, v200
	v_mov_b32_e32 v63, v201
	v_mov_b32_e32 v64, v202
	v_mov_b32_e32 v65, v203
	v_mov_b32_e32 v54, v204
	v_mov_b32_e32 v55, v205
	v_mov_b32_e32 v56, v206
	v_mov_b32_e32 v57, v207
	s_nop 0
	v_mov_b32_e32 v38, v208
	v_mov_b32_e32 v39, v209
	v_mov_b32_e32 v40, v210
	v_mov_b32_e32 v41, v211
	v_mov_b32_e32 v34, v212
	v_mov_b32_e32 v35, v213
	v_mov_b32_e32 v36, v214
	v_mov_b32_e32 v37, v215
	s_waitcnt lgkmcnt(0)
	v_add_f32_e32 v97, v0, v42
	v_fmamk_f32 v113, v97, 0xba800000, v113
	v_fmac_f32_e32 v112, 0xba800000, v97
	v_fmamk_f32 v85, v97, 0xba800000, v85
	v_fmac_f32_e32 v84, 0xba800000, v97
	v_fmamk_f32 v89, v97, 0xba800000, v89
	v_fmac_f32_e32 v88, 0xba800000, v97
	v_fmamk_f32 v87, v97, 0xba800000, v87
	v_fmac_f32_e32 v86, 0xba800000, v97
	v_pk_mul_f32 v[42:43], v[84:85], v[84:85]
	v_pk_mul_f32 v[44:45], v[112:113], v[112:113]
	v_pk_mul_f32 v[46:47], v[86:87], v[86:87]
	v_pk_mul_f32 v[48:49], v[88:89], v[88:89]
	v_fmac_f32_e32 v110, 0xba800000, v97
	v_pk_mov_b32 v[116:117], v[44:45], v[42:43] op_sel:[1,0]
	v_mov_b32_e32 v45, v43
	v_pk_mov_b32 v[42:43], v[48:49], v[46:47] op_sel:[1,0]
	v_mov_b32_e32 v49, v47
	v_fmac_f32_e32 v108, 0xba800000, v97
	v_fmamk_f32 v111, v97, 0xba800000, v111
	v_mul_f32_e32 v0, v110, v110
	v_fmamk_f32 v109, v97, 0xba800000, v109
	v_pk_add_f32 v[44:45], v[116:117], v[44:45]
	v_pk_add_f32 v[42:43], v[42:43], v[48:49]
	v_pk_fma_f32 v[46:47], v[110:111], v[110:111], v[0:1] op_sel_hi:[1,1,0]
	v_mul_f32_e32 v0, v108, v108
	v_pk_add_f32 v[44:45], v[44:45], v[44:45] op_sel_hi:[0,1]
	v_pk_add_f32 v[42:43], v[42:43], v[42:43] op_sel_hi:[0,1]
	v_pk_fma_f32 v[48:49], v[108:109], v[108:109], v[0:1] op_sel_hi:[1,1,0]
	v_fmamk_f32 v105, v97, 0xba800000, v105
	v_fmac_f32_e32 v104, 0xba800000, v97
	v_fmamk_f32 v107, v97, 0xba800000, v107
	v_fmac_f32_e32 v106, 0xba800000, v97
	v_mul_f32_e32 v46, v106, v106
	v_mul_f32_e32 v48, v107, v107
	v_mul_f32_e32 v44, v104, v104
	v_mul_f32_e32 v42, v105, v105
	v_pk_add_f32 v[46:47], v[46:47], v[48:49]
	v_pk_add_f32 v[42:43], v[44:45], v[42:43]
	s_nop 0
	v_pk_add_f32 v[42:43], v[46:47], v[42:43]
	s_nop 0
	v_add_f32_e32 v0, v42, v43
	v_mov_b32_e32 v46, v216
	v_mov_b32_e32 v47, v217
	v_mov_b32_e32 v48, v218
	v_mov_b32_e32 v49, v219
	v_mov_b32_e32 v42, v220
	v_mov_b32_e32 v43, v221
	v_mov_b32_e32 v44, v222
	v_mov_b32_e32 v45, v223
	ds_bpermute_b32 v97, v233, v0
	s_waitcnt lgkmcnt(0)
	v_add_f32_e32 v0, v0, v97
	ds_bpermute_b32 v97, v234, v0
	s_waitcnt lgkmcnt(0)
	v_add_f32_e32 v0, v0, v97
	ds_bpermute_b32 v97, v235, v0
	s_waitcnt lgkmcnt(0)
	v_add_f32_e32 v0, v0, v97
	ds_bpermute_b32 v97, v236, v0
	s_waitcnt lgkmcnt(0)
	v_add_f32_e32 v0, v0, v97
	ds_bpermute_b32 v97, v237, v0
	s_waitcnt lgkmcnt(0)
	v_add_f32_e32 v0, v0, v97
	ds_bpermute_b32 v97, v238, v0
	s_waitcnt lgkmcnt(0)
	v_add_f32_e32 v0, v0, v97
	v_fmamk_f32 v0, v0, 0x3a800000, v243
	v_mul_f32_e32 v97, 0x4f800000, v0
	v_cmp_gt_f32_e32 vcc, s37, v0
	s_nop 1
	v_cndmask_b32_e32 v0, v0, v97, vcc
	v_sqrt_f32_e32 v97, v0
	s_nop 0
	v_add_u32_e32 v99, -1, v97
	v_add_u32_e32 v101, 1, v97
	v_fma_f32 v114, -v99, v97, v0
	v_fma_f32 v115, -v101, v97, v0
	v_cmp_ge_f32_e64 s[0:1], 0, v114
	s_nop 1
	v_cndmask_b32_e64 v97, v97, v99, s[0:1]
	v_cmp_lt_f32_e64 s[0:1], 0, v115
	v_lshl_add_u64 v[114:115], v[94:95], 0, v[82:83]
	s_nop 0
	v_cndmask_b32_e64 v97, v97, v101, s[0:1]
	v_mul_f32_e32 v99, 0x37800000, v97
	v_cndmask_b32_e32 v97, v97, v99, vcc
	v_cmp_class_f32_e32 vcc, v0, v242
	s_nop 1
	v_cndmask_b32_e32 v0, v97, v0, vcc
	v_div_scale_f32 v97, s[0:1], v0, v0, 1.0
	v_rcp_f32_e32 v99, v97
	v_div_scale_f32 v82, vcc, 1.0, v0, 1.0
	v_fma_f32 v83, -v97, v99, 1.0
	v_fmac_f32_e32 v99, v83, v99
	v_mul_f32_e32 v83, v82, v99
	v_fma_f32 v101, -v97, v83, v82
	v_fmac_f32_e32 v83, v101, v99
	v_fma_f32 v82, -v97, v83, v82
	v_div_fmas_f32 v82, v82, v99, v83
	v_div_fixup_f32 v116, v82, v0, 1.0
	v_pk_mul_f32 v[82:83], v[112:113], v[116:117] op_sel_hi:[1,0]
	v_pk_mul_f32 v[84:85], v[84:85], v[116:117] op_sel_hi:[1,0]
	v_pk_mul_f32 v[112:113], v[88:89], v[116:117] op_sel_hi:[1,0]
	v_pk_mul_f32 v[86:87], v[86:87], v[116:117] op_sel_hi:[1,0]
	v_cndmask_b32_e64 v0, 0, 1, s[28:29]
	v_pk_fma_f32 v[84:85], v[12:13], v[84:85], v[16:17]
	v_pk_fma_f32 v[82:83], v[10:11], v[82:83], v[14:15]
	v_pk_fma_f32 v[88:89], v[4:5], v[86:87], v[8:9]
	v_cmp_ne_u32_e64 s[0:1], 1, v0
	s_andn2_b64 vcc, exec, s[28:29]
	v_pk_fma_f32 v[86:87], v[2:3], v[112:113], v[6:7]
	s_cbranch_vccnz .LBB0_588
	global_store_dwordx4 v[114:115], v[82:85], off
	global_store_dwordx4 v[114:115], v[86:89], off offset:16
